# GEMM K-loop: the address arithmetic of MFMA blocks 2 and 6 moved below their closing barrier into the next LDS section (instead of the MFMA shadow)
# baseline (speedup 1.0000x reference)
; #define LDA(dst, b, h) for (int m = 0; m < 4; ++m) for (int k = 0; k < 2; ++k) \
;     dst[m][k] = *reinterpret_cast<const bf16x8*>(SA(b, h) + lds_byte(wr * 64 + m * 16 + fr, k * 32 + fq * 8))
; #define LDB(dst, b, h) for (int n = 0; n < 2; ++n) for (int k = 0; k < 2; ++k) \
;     dst[n][k] = *reinterpret_cast<const bf16x8*>(SB(b, h) + lds_byte(wc * 32 + n * 16 + fr, k * 32 + fq * 8))
; #define MMA(ai, bj, At_, Bt_) do { __builtin_amdgcn_s_setprio(1); \
;     for (int m = 0; m < 4; ++m) for (int n = 0; n < 2; ++n) for (int k = 0; k < 2; ++k) \
;       acc[ai][bj][m][n] = __builtin_amdgcn_mfma_f32_16x16x32_bf16(Bt_[n][k], At_[m][k], acc[ai][bj][m][n], 0, 0, 0); \
;     __builtin_amdgcn_s_setprio(0); } while (0)
; #define WAIT_L(n) asm volatile("s_waitcnt lgkmcnt(" #n ")" ::: "memory")
; #define BAR __builtin_amdgcn_s_barrier()
; #define SCHED __builtin_amdgcn_sched_barrier(0)
; #define STG(P, PTR, LD, O0) do { const bf16_t* _g = (PTR); \
;     __builtin_amdgcn_global_load_lds((const unsigned*)(_g + O0), (lds_u32*)((P) + swave * 1024), 16, 0, 0); \
;     __builtin_amdgcn_global_load_lds((const unsigned*)(_g + (size_t)64 * (LD) + O0), (lds_u32*)((P) + swave * 1024 + 8192), 16, 0, 0); } while (0)
; #define LDA(dst, b, h) for (int m = 0; m < 4; ++m) for (int k = 0; k < 2; ++k) \
;     dst[m][k] = *reinterpret_cast<const bf16x8*>(SA(b, h) + lds_byte(wr * 64 + m * 16 + fr, k * 32 + fq * 8))
; #define LDB(dst, b, h) for (int n = 0; n < 2; ++n) for (int k = 0; k < 2; ++k) \
;     dst[n][k] = *reinterpret_cast<const bf16x8*>(SB(b, h) + lds_byte(wc * 32 + n * 16 + fr, k * 32 + fq * 8))
; __device__ __forceinline__ void gemm_stream(int swave, const GemmJob& J, char* shm, int vb, int G) {
;     ...
;       const bool last = (t == nt - 2);
;       const bf16_t* xA = last ? nA : cA; const bf16_t* xA1 = last ? nA1 : cA1; const int k2 = last ? 0 : t + 2;
;       const bf16_t* b2 = last ? nB : cB + (size_t)(t + 2) * 64; const bf16_t* b3 = b2 + 64;
;       LDB(B0, 0, 0); SCHED; LDA(At, 0, 0); STGA(SA(1, 1), cA, cA1, t + 1, 1);
;       WAIT_L(8); BAR; WAIT_L(0); MMA(0, 0, At, B0); BAR; SCHED;
;       LDB(B1, 0, 1); STG(SB(0, 0), b2, ldb, offB0);
;       BAR; WAIT_L(0); MMA(0, 1, At, B1); BAR;
;       LDA(At, 0, 1); STGA(SA(0, 0), xA, xA1, k2, 0);
;       BAR; WAIT_L(0); MMA(1, 0, At, B0); BAR; SCHED;
;       STG(SB(0, 1), b2 + hB, ldb, offB0);
.LBB0_729:
	ds_read_b128 v[164:167], v139
	ds_read_b128 v[168:171], v139 offset:1024
	ds_read_b128 v[172:175], v139 offset:2048
	ds_read_b128 v[176:179], v139 offset:3072
	s_cmp_eq_u32 s49, s29
	s_cselect_b64 s[68:69], -1, 0
	s_and_b64 s[64:65], s[68:69], exec
	s_cselect_b32 s52, s10, s8
	s_cselect_b32 s64, s11, s9
	s_add_i32 s33, s2, 2
	s_and_b64 s[68:69], s[68:69], exec
	s_cselect_b32 s71, s15, s21
	s_cselect_b32 s70, s14, s20
	s_cselect_b32 s68, 0, s33
	s_cselect_b32 s65, s12, s16
	s_cselect_b32 s66, s13, s17
	s_or_b32 s2, s2, 1
	s_cmp_lt_u32 s2, s36
	s_cselect_b64 vcc, -1, 0
	s_and_b64 s[2:3], vcc, exec
	s_cselect_b32 s3, 0, s36
	s_cselect_b32 s2, s38, s37
	s_not_b32 s3, s3
	s_add_i32 s94, s3, s29
	s_and_b64 s[72:73], vcc, exec
	s_cselect_b32 s3, s9, s17
	s_cselect_b32 s69, s8, s16
	s_lshl_b64 s[72:73], s[94:95], 7
	s_add_u32 s69, s69, s72
	s_addc_u32 s74, s3, s73
	s_mov_b32 s3, s95
	s_lshl_b64 s[72:73], s[2:3], 8
	s_add_u32 s72, s69, s72
	v_cndmask_b32_e32 v2, v138, v0, vcc
	s_addc_u32 s73, s74, s73
	s_add_i32 m0, s42, 0xc000
	s_lshl_b64 s[2:3], s[2:3], 7
	v_lshlrev_b64 v[212:213], 1, v[2:3]
	s_add_u32 s2, s72, s2
	v_lshl_add_u64 v[214:215], s[72:73], 0, v[212:213]
	s_addc_u32 s3, s73, s3
	ds_read_b128 v[180:183], v144
	ds_read_b128 v[188:191], v145
	ds_read_b128 v[196:199], v159
	ds_read_b128 v[204:207], v160
	global_load_lds_dwordx4 v[214:215], off
	v_lshl_add_u64 v[212:213], s[2:3], 0, v[212:213]
	s_add_i32 m0, s42, 0xe000
	s_nop 0
	global_load_lds_dwordx4 v[212:213], off
	s_waitcnt lgkmcnt(4)
	s_barrier
	s_waitcnt lgkmcnt(0)
	v_mfma_f32_16x16x32_bf16 v[128:131], v[164:167], v[180:183], v[128:131]
	ds_read_b128 v[184:187], v144 offset:1024
	v_mfma_f32_16x16x32_bf16 v[124:127], v[172:175], v[180:183], v[124:127]
	ds_read_b128 v[192:195], v145 offset:1024
	v_mfma_f32_16x16x32_bf16 v[120:123], v[164:167], v[188:191], v[120:123]
	ds_read_b128 v[200:203], v159 offset:1024
	v_mfma_f32_16x16x32_bf16 v[116:119], v[172:175], v[188:191], v[116:119]
	ds_read_b128 v[208:211], v160 offset:1024
	v_mfma_f32_16x16x32_bf16 v[104:107], v[164:167], v[196:199], v[104:107]
	v_mfma_f32_16x16x32_bf16 v[100:103], v[172:175], v[196:199], v[100:103]
	v_mfma_f32_16x16x32_bf16 v[88:91], v[164:167], v[204:207], v[88:91]
	v_mfma_f32_16x16x32_bf16 v[84:87], v[172:175], v[204:207], v[84:87]
	s_waitcnt lgkmcnt(0)
	v_mfma_f32_16x16x32_bf16 v[128:131], v[168:171], v[184:187], v[128:131]
	v_mfma_f32_16x16x32_bf16 v[124:127], v[176:179], v[184:187], v[124:127]
	v_mfma_f32_16x16x32_bf16 v[120:123], v[168:171], v[192:195], v[120:123]
	v_mfma_f32_16x16x32_bf16 v[116:119], v[176:179], v[192:195], v[116:119]
	v_mfma_f32_16x16x32_bf16 v[104:107], v[168:171], v[200:203], v[104:107]
	v_mfma_f32_16x16x32_bf16 v[100:103], v[176:179], v[200:203], v[100:103]
	v_mfma_f32_16x16x32_bf16 v[88:91], v[168:171], v[208:211], v[88:91]
	v_mfma_f32_16x16x32_bf16 v[84:87], v[176:179], v[208:211], v[84:87]
	s_barrier
	s_add_u32 s2, s70, s0
	s_mov_b32 m0, s43
	v_lshl_add_u64 v[228:229], s[70:71], 0, v[136:137]
	s_addc_u32 s3, s71, s1
	ds_read_b128 v[212:215], v161
	ds_read_b128 v[216:219], v161 offset:1024
	ds_read_b128 v[220:223], v161 offset:2048
	ds_read_b128 v[224:227], v161 offset:3072
	global_load_lds_dwordx4 v[228:229], off
	v_lshl_add_u64 v[230:231], s[2:3], 0, v[136:137]
	s_mov_b32 m0, s44
	s_nop 0
	global_load_lds_dwordx4 v[230:231], off
	s_barrier
	s_waitcnt lgkmcnt(0)
	v_mfma_f32_16x16x32_bf16 v[112:115], v[212:215], v[180:183], v[112:115]
	v_mfma_f32_16x16x32_bf16 v[108:111], v[220:223], v[180:183], v[108:111]
	v_mfma_f32_16x16x32_bf16 v[96:99], v[212:215], v[188:191], v[96:99]
	v_mfma_f32_16x16x32_bf16 v[92:95], v[220:223], v[188:191], v[92:95]
	v_mfma_f32_16x16x32_bf16 v[80:83], v[212:215], v[196:199], v[80:83]
	v_mfma_f32_16x16x32_bf16 v[76:79], v[220:223], v[196:199], v[76:79]
	v_mfma_f32_16x16x32_bf16 v[72:75], v[212:215], v[204:207], v[72:75]
	v_mfma_f32_16x16x32_bf16 v[68:71], v[220:223], v[204:207], v[68:71]
	v_mfma_f32_16x16x32_bf16 v[112:115], v[216:219], v[184:187], v[112:115]
	v_mfma_f32_16x16x32_bf16 v[108:111], v[224:227], v[184:187], v[108:111]
	v_mfma_f32_16x16x32_bf16 v[96:99], v[216:219], v[192:195], v[96:99]
	v_mfma_f32_16x16x32_bf16 v[92:95], v[224:227], v[192:195], v[92:95]
	v_mfma_f32_16x16x32_bf16 v[80:83], v[216:219], v[200:203], v[80:83]
	v_mfma_f32_16x16x32_bf16 v[76:79], v[224:227], v[200:203], v[76:79]
	v_mfma_f32_16x16x32_bf16 v[72:75], v[216:219], v[208:211], v[72:75]
	v_mfma_f32_16x16x32_bf16 v[68:71], v[224:227], v[208:211], v[68:71]
	s_barrier
	ds_read_b128 v[180:183], v144 offset:16384
	ds_read_b128 v[188:191], v145 offset:16384
	ds_read_b128 v[196:199], v159 offset:16384
	ds_read_b128 v[204:207], v160 offset:16384
	s_cmp_lt_u32 s68, s36
	s_cselect_b64 vcc, -1, 0
	s_and_b64 s[70:71], vcc, exec
	s_cselect_b32 s70, s38, s37
	s_sub_i32 s69, s68, s36
	s_min_u32 s94, s68, s69
	s_and_b64 s[72:73], vcc, exec
	s_cselect_b32 s69, s64, s66
	s_cselect_b32 s71, s52, s65
	s_lshl_b64 s[72:73], s[94:95], 7
	v_cndmask_b32_e32 v2, v138, v0, vcc
	s_add_u32 s72, s71, s72
	s_mov_b32 s71, s95
	s_addc_u32 s73, s69, s73
	v_lshlrev_b64 v[232:233], 1, v[2:3]
	s_lshl_b64 s[70:71], s[70:71], 7
	v_lshl_add_u64 v[234:235], s[72:73], 0, v[232:233]
	s_add_u32 s72, s72, s70
	s_mov_b32 m0, s42
	s_addc_u32 s73, s73, s71
	global_load_lds_dwordx4 v[234:235], off
	v_lshl_add_u64 v[234:235], s[72:73], 0, v[232:233]
	s_mov_b32 m0, s39
	s_nop 0
	global_load_lds_dwordx4 v[234:235], off
	s_barrier
; #define LDA(dst, b, h) for (int m = 0; m < 4; ++m) for (int k = 0; k < 2; ++k) \
;     dst[m][k] = *reinterpret_cast<const bf16x8*>(SA(b, h) + lds_byte(wr * 64 + m * 16 + fr, k * 32 + fq * 8))
; #define LDB(dst, b, h) for (int n = 0; n < 2; ++n) for (int k = 0; k < 2; ++k) \
;     dst[n][k] = *reinterpret_cast<const bf16x8*>(SB(b, h) + lds_byte(wc * 32 + n * 16 + fr, k * 32 + fq * 8))
; #define MMA(ai, bj, At_, Bt_) do { __builtin_amdgcn_s_setprio(1); \
;     for (int m = 0; m < 4; ++m) for (int n = 0; n < 2; ++n) for (int k = 0; k < 2; ++k) \
;       acc[ai][bj][m][n] = __builtin_amdgcn_mfma_f32_16x16x32_bf16(Bt_[n][k], At_[m][k], acc[ai][bj][m][n], 0, 0, 0); \
;     __builtin_amdgcn_s_setprio(0); } while (0)
; #define WAIT_V(n) asm volatile("s_waitcnt vmcnt(" #n ")" ::: "memory")
; #define WAIT_L(n) asm volatile("s_waitcnt lgkmcnt(" #n ")" ::: "memory")
; #define BAR __builtin_amdgcn_s_barrier()
; #define SCHED __builtin_amdgcn_sched_barrier(0)
; #define STG(P, PTR, LD, O0) do { const bf16_t* _g = (PTR); \
;     __builtin_amdgcn_global_load_lds((const unsigned*)(_g + O0), (lds_u32*)((P) + swave * 1024), 16, 0, 0); \
;     __builtin_amdgcn_global_load_lds((const unsigned*)(_g + (size_t)64 * (LD) + O0), (lds_u32*)((P) + swave * 1024 + 8192), 16, 0, 0); } while (0)
; #define LDA(dst, b, h) for (int m = 0; m < 4; ++m) for (int k = 0; k < 2; ++k) \
;     dst[m][k] = *reinterpret_cast<const bf16x8*>(SA(b, h) + lds_byte(wr * 64 + m * 16 + fr, k * 32 + fq * 8))
; #define LDB(dst, b, h) for (int n = 0; n < 2; ++n) for (int k = 0; k < 2; ++k) \
;     dst[n][k] = *reinterpret_cast<const bf16x8*>(SB(b, h) + lds_byte(wc * 32 + n * 16 + fr, k * 32 + fq * 8))
; #define WAIT_V(n) asm volatile("s_waitcnt vmcnt(" #n ")" ::: "memory")
; #define WAIT_L(n) asm volatile("s_waitcnt lgkmcnt(" #n ")" ::: "memory")
; #define BAR __builtin_amdgcn_s_barrier()
; #define SCHED __builtin_amdgcn_sched_barrier(0)
; __device__ __forceinline__ void gemm_stream(int swave, const GemmJob& J, char* shm, int vb, int G) {
;     ...
;       BAR; WAIT_L(0); MMA(1, 0, At, B0); BAR; SCHED;
;       STG(SB(0, 1), b2 + hB, ldb, offB0);
;       WAIT_V(6); BAR; MMA(1, 1, At, B1); BAR;
;       LDB(B0, 1, 0); SCHED; LDA(At, 1, 0); STGA(SA(0, 1), xA, xA1, k2, 1);
;       WAIT_L(8); BAR; WAIT_L(0); MMA(0, 0, At, B0); BAR; SCHED;
;       LDB(B1, 1, 1); STG(SB(1, 0), b3, ldb, offB0);
	s_waitcnt lgkmcnt(0)
	v_mfma_f32_16x16x32_bf16 v[64:67], v[164:167], v[180:183], v[64:67]
	ds_read_b128 v[184:187], v144 offset:17408
	v_mfma_f32_16x16x32_bf16 v[60:63], v[172:175], v[180:183], v[60:63]
	ds_read_b128 v[192:195], v145 offset:17408
	v_mfma_f32_16x16x32_bf16 v[56:59], v[164:167], v[188:191], v[56:59]
	ds_read_b128 v[200:203], v159 offset:17408
	v_mfma_f32_16x16x32_bf16 v[52:55], v[172:175], v[188:191], v[52:55]
	ds_read_b128 v[208:211], v160 offset:17408
	v_mfma_f32_16x16x32_bf16 v[40:43], v[164:167], v[196:199], v[40:43]
	v_mfma_f32_16x16x32_bf16 v[36:39], v[172:175], v[196:199], v[36:39]
	v_mfma_f32_16x16x32_bf16 v[24:27], v[164:167], v[204:207], v[24:27]
	v_mfma_f32_16x16x32_bf16 v[20:23], v[172:175], v[204:207], v[20:23]
	s_waitcnt lgkmcnt(0)
	v_mfma_f32_16x16x32_bf16 v[64:67], v[168:171], v[184:187], v[64:67]
	v_mfma_f32_16x16x32_bf16 v[60:63], v[176:179], v[184:187], v[60:63]
	v_mfma_f32_16x16x32_bf16 v[56:59], v[168:171], v[192:195], v[56:59]
	v_mfma_f32_16x16x32_bf16 v[52:55], v[176:179], v[192:195], v[52:55]
	v_mfma_f32_16x16x32_bf16 v[40:43], v[168:171], v[200:203], v[40:43]
	v_mfma_f32_16x16x32_bf16 v[36:39], v[176:179], v[200:203], v[36:39]
	v_mfma_f32_16x16x32_bf16 v[24:27], v[168:171], v[208:211], v[24:27]
	v_mfma_f32_16x16x32_bf16 v[20:23], v[176:179], v[208:211], v[20:23]
	s_barrier
	s_add_u32 s2, s2, s0
	s_addc_u32 s3, s3, s1
	v_lshl_add_u64 v[234:235], s[2:3], 0, v[136:137]
	s_add_u32 s2, s2, s0
	s_mov_b32 m0, s45
	s_addc_u32 s3, s3, s1
	global_load_lds_dwordx4 v[234:235], off
	v_lshl_add_u64 v[236:237], s[2:3], 0, v[136:137]
	s_mov_b32 m0, s46
	s_nop 0
	global_load_lds_dwordx4 v[236:237], off
	s_waitcnt vmcnt(6)
	s_barrier
	v_mfma_f32_16x16x32_bf16 v[48:51], v[212:215], v[180:183], v[48:51]
	v_mfma_f32_16x16x32_bf16 v[44:47], v[220:223], v[180:183], v[44:47]
	v_mfma_f32_16x16x32_bf16 v[32:35], v[212:215], v[188:191], v[32:35]
	v_mfma_f32_16x16x32_bf16 v[28:31], v[220:223], v[188:191], v[28:31]
	v_mfma_f32_16x16x32_bf16 v[16:19], v[212:215], v[196:199], v[16:19]
	v_mfma_f32_16x16x32_bf16 v[12:15], v[220:223], v[196:199], v[12:15]
	v_mfma_f32_16x16x32_bf16 v[8:11], v[212:215], v[204:207], v[8:11]
	v_mfma_f32_16x16x32_bf16 v[4:7], v[220:223], v[204:207], v[4:7]
	v_mfma_f32_16x16x32_bf16 v[48:51], v[216:219], v[184:187], v[48:51]
	v_mfma_f32_16x16x32_bf16 v[44:47], v[224:227], v[184:187], v[44:47]
	v_mfma_f32_16x16x32_bf16 v[32:35], v[216:219], v[192:195], v[32:35]
	v_mfma_f32_16x16x32_bf16 v[28:31], v[224:227], v[192:195], v[28:31]
	v_mfma_f32_16x16x32_bf16 v[16:19], v[216:219], v[200:203], v[16:19]
	v_mfma_f32_16x16x32_bf16 v[12:15], v[224:227], v[200:203], v[12:15]
	v_mfma_f32_16x16x32_bf16 v[8:11], v[216:219], v[208:211], v[8:11]
	v_mfma_f32_16x16x32_bf16 v[4:7], v[224:227], v[208:211], v[4:7]
	s_barrier
	ds_read_b128 v[164:167], v162
	ds_read_b128 v[168:171], v162 offset:1024
	ds_read_b128 v[172:175], v162 offset:2048
	ds_read_b128 v[176:179], v162 offset:3072
	s_add_u32 s2, s72, s70
	s_addc_u32 s3, s73, s71
	v_lshl_add_u64 v[212:213], s[2:3], 0, v[232:233]
	s_add_u32 s2, s2, s70
	s_mov_b32 m0, s47
	s_addc_u32 s3, s3, s71
	ds_read_b128 v[180:183], v144 offset:32768
	ds_read_b128 v[188:191], v145 offset:32768
	ds_read_b128 v[196:199], v159 offset:32768
	ds_read_b128 v[204:207], v160 offset:32768
	global_load_lds_dwordx4 v[212:213], off
	v_lshl_add_u64 v[212:213], s[2:3], 0, v[232:233]
	s_mov_b32 m0, s48
	s_nop 0
	global_load_lds_dwordx4 v[212:213], off
	s_waitcnt lgkmcnt(4)
	s_barrier
	s_waitcnt lgkmcnt(0)
	v_mfma_f32_16x16x32_bf16 v[128:131], v[164:167], v[180:183], v[128:131]
	ds_read_b128 v[184:187], v144 offset:33792
	v_mfma_f32_16x16x32_bf16 v[124:127], v[172:175], v[180:183], v[124:127]
	ds_read_b128 v[192:195], v145 offset:33792
	v_mfma_f32_16x16x32_bf16 v[120:123], v[164:167], v[188:191], v[120:123]
	ds_read_b128 v[200:203], v159 offset:33792
	v_mfma_f32_16x16x32_bf16 v[116:119], v[172:175], v[188:191], v[116:119]
	ds_read_b128 v[208:211], v160 offset:33792
	v_mfma_f32_16x16x32_bf16 v[104:107], v[164:167], v[196:199], v[104:107]
	v_mfma_f32_16x16x32_bf16 v[100:103], v[172:175], v[196:199], v[100:103]
	v_mfma_f32_16x16x32_bf16 v[88:91], v[164:167], v[204:207], v[88:91]
	v_mfma_f32_16x16x32_bf16 v[84:87], v[172:175], v[204:207], v[84:87]
	s_waitcnt lgkmcnt(0)
	v_mfma_f32_16x16x32_bf16 v[128:131], v[168:171], v[184:187], v[128:131]
	v_mfma_f32_16x16x32_bf16 v[124:127], v[176:179], v[184:187], v[124:127]
	v_mfma_f32_16x16x32_bf16 v[120:123], v[168:171], v[192:195], v[120:123]
	v_mfma_f32_16x16x32_bf16 v[116:119], v[176:179], v[192:195], v[116:119]
	v_mfma_f32_16x16x32_bf16 v[104:107], v[168:171], v[200:203], v[104:107]
	v_mfma_f32_16x16x32_bf16 v[100:103], v[176:179], v[200:203], v[100:103]
	v_mfma_f32_16x16x32_bf16 v[88:91], v[168:171], v[208:211], v[88:91]
	v_mfma_f32_16x16x32_bf16 v[84:87], v[176:179], v[208:211], v[84:87]
	s_barrier
	v_lshl_add_u64 v[228:229], v[228:229], 0, s[22:23]
	s_add_i32 m0, s42, 0x18000
	ds_read_b128 v[212:215], v163
	ds_read_b128 v[216:219], v163 offset:1024
	ds_read_b128 v[220:223], v163 offset:2048
	ds_read_b128 v[224:227], v163 offset:3072
	global_load_lds_dwordx4 v[228:229], off
	v_lshl_add_u64 v[228:229], v[230:231], 0, s[22:23]
	s_add_i32 m0, s42, 0x1a000
	s_nop 0
	global_load_lds_dwordx4 v[228:229], off
	s_barrier
; #define LDA(dst, b, h) for (int m = 0; m < 4; ++m) for (int k = 0; k < 2; ++k) \
;     dst[m][k] = *reinterpret_cast<const bf16x8*>(SA(b, h) + lds_byte(wr * 64 + m * 16 + fr, k * 32 + fq * 8))
; #define MMA(ai, bj, At_, Bt_) do { __builtin_amdgcn_s_setprio(1); \
;     for (int m = 0; m < 4; ++m) for (int n = 0; n < 2; ++n) for (int k = 0; k < 2; ++k) \
;       acc[ai][bj][m][n] = __builtin_amdgcn_mfma_f32_16x16x32_bf16(Bt_[n][k], At_[m][k], acc[ai][bj][m][n], 0, 0, 0); \
;     __builtin_amdgcn_s_setprio(0); } while (0)
; #define WAIT_V(n) asm volatile("s_waitcnt vmcnt(" #n ")" ::: "memory")
; #define WAIT_L(n) asm volatile("s_waitcnt lgkmcnt(" #n ")" ::: "memory")
; #define BAR __builtin_amdgcn_s_barrier()
; #define SCHED __builtin_amdgcn_sched_barrier(0)
; #define STG(P, PTR, LD, O0) do { const bf16_t* _g = (PTR); \
;     __builtin_amdgcn_global_load_lds((const unsigned*)(_g + O0), (lds_u32*)((P) + swave * 1024), 16, 0, 0); \
;     __builtin_amdgcn_global_load_lds((const unsigned*)(_g + (size_t)64 * (LD) + O0), (lds_u32*)((P) + swave * 1024 + 8192), 16, 0, 0); } while (0)
; #define LDA(dst, b, h) for (int m = 0; m < 4; ++m) for (int k = 0; k < 2; ++k) \
;     dst[m][k] = *reinterpret_cast<const bf16x8*>(SA(b, h) + lds_byte(wr * 64 + m * 16 + fr, k * 32 + fq * 8))
; #define MMA(ai, bj, At_, Bt_) do { __builtin_amdgcn_s_setprio(1); \
;     for (int m = 0; m < 4; ++m) for (int n = 0; n < 2; ++n) for (int k = 0; k < 2; ++k) \
;       acc[ai][bj][m][n] = __builtin_amdgcn_mfma_f32_16x16x32_bf16(Bt_[n][k], At_[m][k], acc[ai][bj][m][n], 0, 0, 0); \
;     __builtin_amdgcn_s_setprio(0); } while (0)
; #define WAIT_V(n) asm volatile("s_waitcnt vmcnt(" #n ")" ::: "memory")
; #define WAIT_L(n) asm volatile("s_waitcnt lgkmcnt(" #n ")" ::: "memory")
; #define BAR __builtin_amdgcn_s_barrier()
; #define SCHED __builtin_amdgcn_sched_barrier(0)
; __device__ __forceinline__ void gemm_stream(int swave, const GemmJob& J, char* shm, int vb, int G) {
;     ...
;       BAR; WAIT_L(0); MMA(0, 1, At, B1); BAR;
;       LDA(At, 1, 1); STGA(SA(1, 0), xA, xA1, k2 + 1, 0);
;       BAR; WAIT_L(0); MMA(1, 0, At, B0); BAR; SCHED;
;       STG(SB(1, 1), b3 + hB, ldb, offB0);
;       WAIT_V(6); BAR; MMA(1, 1, At, B1); BAR;
	s_waitcnt lgkmcnt(0)
	v_mfma_f32_16x16x32_bf16 v[112:115], v[212:215], v[180:183], v[112:115]
	v_mfma_f32_16x16x32_bf16 v[108:111], v[220:223], v[180:183], v[108:111]
	v_mfma_f32_16x16x32_bf16 v[96:99], v[212:215], v[188:191], v[96:99]
	v_mfma_f32_16x16x32_bf16 v[92:95], v[220:223], v[188:191], v[92:95]
	v_mfma_f32_16x16x32_bf16 v[80:83], v[212:215], v[196:199], v[80:83]
	v_mfma_f32_16x16x32_bf16 v[76:79], v[220:223], v[196:199], v[76:79]
	v_mfma_f32_16x16x32_bf16 v[72:75], v[212:215], v[204:207], v[72:75]
	v_mfma_f32_16x16x32_bf16 v[68:71], v[220:223], v[204:207], v[68:71]
	v_mfma_f32_16x16x32_bf16 v[112:115], v[216:219], v[184:187], v[112:115]
	v_mfma_f32_16x16x32_bf16 v[108:111], v[224:227], v[184:187], v[108:111]
	v_mfma_f32_16x16x32_bf16 v[96:99], v[216:219], v[192:195], v[96:99]
	v_mfma_f32_16x16x32_bf16 v[92:95], v[224:227], v[192:195], v[92:95]
	v_mfma_f32_16x16x32_bf16 v[80:83], v[216:219], v[200:203], v[80:83]
	v_mfma_f32_16x16x32_bf16 v[76:79], v[224:227], v[200:203], v[76:79]
	v_mfma_f32_16x16x32_bf16 v[72:75], v[216:219], v[208:211], v[72:75]
	v_mfma_f32_16x16x32_bf16 v[68:71], v[224:227], v[208:211], v[68:71]
	s_barrier
	ds_read_b128 v[180:183], v144 offset:49152
	ds_read_b128 v[188:191], v145 offset:49152
	ds_read_b128 v[196:199], v159 offset:49152
	ds_read_b128 v[204:207], v160 offset:49152
	s_or_b32 s68, s68, 1
	s_cmp_lt_u32 s68, s36
	s_cselect_b64 vcc, -1, 0
	s_and_b64 s[2:3], vcc, exec
	s_cselect_b32 s69, s38, s37
	s_sub_i32 s2, s68, s36
	s_min_u32 s94, s68, s2
	s_and_b64 s[2:3], vcc, exec
	s_cselect_b32 s64, s64, s66
	s_cselect_b32 s52, s52, s65
	s_lshl_b64 s[2:3], s[94:95], 7
	v_cndmask_b32_e32 v2, v138, v0, vcc
	s_add_u32 s2, s52, s2
	s_addc_u32 s3, s64, s3
	v_lshlrev_b64 v[228:229], 1, v[2:3]
	s_lshl_b32 s52, s69, 7
	v_lshl_add_u64 v[230:231], s[2:3], 0, v[228:229]
	s_add_u32 s2, s2, s52
	s_mov_b32 m0, s54
	s_addc_u32 s3, s3, 0
	global_load_lds_dwordx4 v[230:231], off
	v_lshl_add_u64 v[228:229], s[2:3], 0, v[228:229]
	s_mov_b32 m0, s55
	s_nop 0
	global_load_lds_dwordx4 v[228:229], off
	s_barrier
	s_waitcnt lgkmcnt(0)
	v_mfma_f32_16x16x32_bf16 v[64:67], v[164:167], v[180:183], v[64:67]
	ds_read_b128 v[184:187], v144 offset:50176
	v_mfma_f32_16x16x32_bf16 v[60:63], v[172:175], v[180:183], v[60:63]
	ds_read_b128 v[192:195], v145 offset:50176
	v_mfma_f32_16x16x32_bf16 v[56:59], v[164:167], v[188:191], v[56:59]
	ds_read_b128 v[200:203], v159 offset:50176
	v_mfma_f32_16x16x32_bf16 v[52:55], v[172:175], v[188:191], v[52:55]
	ds_read_b128 v[208:211], v160 offset:50176
	v_mfma_f32_16x16x32_bf16 v[40:43], v[164:167], v[196:199], v[40:43]
	v_mfma_f32_16x16x32_bf16 v[36:39], v[172:175], v[196:199], v[36:39]
	v_mfma_f32_16x16x32_bf16 v[24:27], v[164:167], v[204:207], v[24:27]
	v_mfma_f32_16x16x32_bf16 v[20:23], v[172:175], v[204:207], v[20:23]
	s_waitcnt lgkmcnt(0)
	v_mfma_f32_16x16x32_bf16 v[64:67], v[168:171], v[184:187], v[64:67]
	v_mfma_f32_16x16x32_bf16 v[60:63], v[176:179], v[184:187], v[60:63]
	v_mfma_f32_16x16x32_bf16 v[56:59], v[168:171], v[192:195], v[56:59]
	v_mfma_f32_16x16x32_bf16 v[52:55], v[176:179], v[192:195], v[52:55]
	v_mfma_f32_16x16x32_bf16 v[40:43], v[168:171], v[200:203], v[40:43]
	v_mfma_f32_16x16x32_bf16 v[36:39], v[176:179], v[200:203], v[36:39]
	v_mfma_f32_16x16x32_bf16 v[24:27], v[168:171], v[208:211], v[24:27]
	v_mfma_f32_16x16x32_bf16 v[20:23], v[176:179], v[208:211], v[20:23]
	s_barrier
	v_lshl_add_u64 v[164:165], v[234:235], 0, s[22:23]
	s_add_i32 m0, s42, 0x1c000
	s_nop 0
	global_load_lds_dwordx4 v[164:165], off
	v_lshl_add_u64 v[164:165], v[236:237], 0, s[22:23]
	s_add_i32 m0, s42, 0x1e000
	s_nop 0
	global_load_lds_dwordx4 v[164:165], off
	s_waitcnt vmcnt(6)
	s_barrier
	v_mfma_f32_16x16x32_bf16 v[48:51], v[212:215], v[180:183], v[48:51]
	v_mfma_f32_16x16x32_bf16 v[44:47], v[220:223], v[180:183], v[44:47]
	s_add_i32 s29, s29, 2
	v_mfma_f32_16x16x32_bf16 v[32:35], v[212:215], v[188:191], v[32:35]
	s_add_u32 s20, s20, 0x100
	v_mfma_f32_16x16x32_bf16 v[28:31], v[220:223], v[188:191], v[28:31]
	s_addc_u32 s21, s21, 0
	v_mfma_f32_16x16x32_bf16 v[16:19], v[212:215], v[196:199], v[16:19]
	s_cmp_ge_u32 s33, s49
	v_mfma_f32_16x16x32_bf16 v[12:15], v[220:223], v[196:199], v[12:15]
	s_mov_b32 s2, s33
	v_mfma_f32_16x16x32_bf16 v[8:11], v[212:215], v[204:207], v[8:11]
	v_mfma_f32_16x16x32_bf16 v[4:7], v[220:223], v[204:207], v[4:7]
	v_mfma_f32_16x16x32_bf16 v[48:51], v[216:219], v[184:187], v[48:51]
	v_mfma_f32_16x16x32_bf16 v[44:47], v[224:227], v[184:187], v[44:47]
	v_mfma_f32_16x16x32_bf16 v[32:35], v[216:219], v[192:195], v[32:35]
	v_mfma_f32_16x16x32_bf16 v[28:31], v[224:227], v[192:195], v[28:31]
	v_mfma_f32_16x16x32_bf16 v[16:19], v[216:219], v[200:203], v[16:19]
	v_mfma_f32_16x16x32_bf16 v[12:15], v[224:227], v[200:203], v[12:15]
	v_mfma_f32_16x16x32_bf16 v[8:11], v[216:219], v[208:211], v[8:11]
	v_mfma_f32_16x16x32_bf16 v[4:7], v[224:227], v[208:211], v[4:7]
	s_barrier
; __device__ __forceinline__ unsigned pk2(float lo, float hi) { f32x2_t v = {lo, hi}; bf16x2_t b = __builtin_convertvector(v, bf16x2_t); return __builtin_bit_cast(unsigned, b); }
; #define WAIT_V(n) asm volatile("s_waitcnt vmcnt(" #n ")" ::: "memory")
; #define BAR __builtin_amdgcn_s_barrier()
; #define WAIT_V(n) asm volatile("s_waitcnt vmcnt(" #n ")" ::: "memory")
; #define BAR __builtin_amdgcn_s_barrier()
; __device__ __forceinline__ void gemm_stream(int swave, const GemmJob& J, char* shm, int vb, int G) {
;     ...
;     {
;       bf16_t* C = (bf16_t*)((char*)J.c0 + (size_t)cg * J.strideC);
; #pragma unroll
;       for (int ai = 0; ai < 2; ++ai)
; #pragma unroll
;         for (int m = 0; m < 4; ++m)
; #pragma unroll
;           for (int bj = 0; bj < 2; ++bj) {
;             const f32x4 v0 = acc[ai][bj][m][0], v1 = acc[ai][bj][m][1];
;             uint4 o; o.x = pk2(v0[0], v0[1]); o.y = pk2(v0[2], v0[3]); o.z = pk2(v1[0], v1[1]); o.w = pk2(v1[2], v1[3]);
;             *(uint4*)(C + (size_t)(cbrow + ai * 128 + wr * 64 + m * 16 + fr) * J.ldc + cbcol + bj * 128 + wc * 32 + fq * 8) = o;
;           }
;     }
;     if (!has_next) break;
; #pragma unroll
;     for (int a_ = 0; a_ < 2; ++a_)
; #pragma unroll
;       for (int b_ = 0; b_ < 2; ++b_)
; #pragma unroll
;         for (int m = 0; m < 4; ++m)
; #pragma unroll
;           for (int n = 0; n < 2; ++n) acc[a_][b_][m][n] = (f32x4){0.f, 0.f, 0.f, 0.f};
;     id = nid; cg = ng; cbrow = nbrow; cbcol = nbcol; cA = nA; cA1 = nA1; cB = nB;
;   }
;   WAIT_V(0);
;   if (wr == 0) BAR;
	s_cbranch_scc0 .LBB0_729
	v_add_u32_e32 v164, s5, v1
	s_ashr_i32 s5, s4, 31
	s_lshl_b64 s[2:3], s[4:5], 1
	v_ashrrev_i32_e32 v2, 31, v164
	s_add_u32 s2, s50, s2
	v_cvt_pk_bf16_f32 v128, v128, v129
	v_cvt_pk_bf16_f32 v129, v130, v131
	v_cvt_pk_bf16_f32 v130, v124, v125
	v_mul_lo_u32 v2, v2, s18
	v_mad_u64_u32 v[124:125], s[4:5], v164, s18, 0
	s_addc_u32 s3, s51, s3
	v_add_u32_e32 v125, v125, v2
	v_lshl_add_u64 v[124:125], v[124:125], 1, s[2:3]
	v_mov_b32_e32 v141, v3
	v_lshl_add_u64 v[124:125], v[124:125], 0, v[140:141]
	v_mov_b32_e32 v143, v3
	v_lshl_add_u64 v[124:125], v[124:125], 0, v[142:143]
	s_lshl_b32 s2, s18, 5
	s_mov_b32 s3, 0
	s_mul_i32 s4, s18, 0xa0
	s_mov_b32 s5, 0
	v_cvt_pk_bf16_f32 v112, v112, v113
	v_cvt_pk_bf16_f32 v113, v114, v115
	v_cvt_pk_bf16_f32 v114, v108, v109
	v_cvt_pk_bf16_f32 v115, v110, v111
	global_store_dwordx4 v[124:125], v[112:115], off offset:256
	v_cvt_pk_bf16_f32 v131, v126, v127
	v_cvt_pk_bf16_f32 v96, v96, v97
	v_lshl_add_u64 v[112:113], v[124:125], 0, s[2:3]
	v_cvt_pk_bf16_f32 v97, v98, v99
	v_cvt_pk_bf16_f32 v98, v92, v93
	v_cvt_pk_bf16_f32 v99, v94, v95
	global_store_dwordx4 v[124:125], v[128:131], off
	global_store_dwordx4 v[112:113], v[96:99], off offset:256
	v_cvt_pk_bf16_f32 v108, v120, v121
	v_cvt_pk_bf16_f32 v109, v122, v123
	v_lshl_add_u64 v[96:97], v[112:113], 0, s[2:3]
	v_cvt_pk_bf16_f32 v110, v116, v117
	v_cvt_pk_bf16_f32 v111, v118, v119
	v_cvt_pk_bf16_f32 v80, v80, v81
	v_cvt_pk_bf16_f32 v81, v82, v83
	v_cvt_pk_bf16_f32 v82, v76, v77
	v_cvt_pk_bf16_f32 v83, v78, v79
	global_store_dwordx4 v[112:113], v[108:111], off
	global_store_dwordx4 v[96:97], v[80:83], off offset:256
	v_cvt_pk_bf16_f32 v64, v64, v65
	v_cvt_pk_bf16_f32 v65, v66, v67
	v_lshl_add_u64 v[80:81], v[96:97], 0, s[2:3]
	v_cvt_pk_bf16_f32 v66, v60, v61
	v_lshl_add_u64 v[60:61], v[80:81], 0, s[4:5]
	v_cvt_pk_bf16_f32 v72, v72, v73
	v_cvt_pk_bf16_f32 v73, v74, v75
	v_cvt_pk_bf16_f32 v74, v68, v69
	v_cvt_pk_bf16_f32 v67, v62, v63
	v_cvt_pk_bf16_f32 v92, v104, v105
	v_cvt_pk_bf16_f32 v93, v106, v107
	v_cvt_pk_bf16_f32 v94, v100, v101
	v_cvt_pk_bf16_f32 v95, v102, v103
	v_cvt_pk_bf16_f32 v76, v88, v89
	v_cvt_pk_bf16_f32 v77, v90, v91
	v_cvt_pk_bf16_f32 v78, v84, v85
	v_cvt_pk_bf16_f32 v79, v86, v87
	v_cvt_pk_bf16_f32 v75, v70, v71
	v_cvt_pk_bf16_f32 v48, v48, v49
	v_cvt_pk_bf16_f32 v49, v50, v51
	v_cvt_pk_bf16_f32 v50, v44, v45
	v_cvt_pk_bf16_f32 v51, v46, v47
	global_store_dwordx4 v[96:97], v[92:95], off
	global_store_dwordx4 v[80:81], v[76:79], off
	global_store_dwordx4 v[80:81], v[72:75], off offset:256
	global_store_dwordx4 v[60:61], v[48:51], off offset:256
	v_cvt_pk_bf16_f32 v32, v32, v33
	v_cvt_pk_bf16_f32 v33, v34, v35
	v_lshl_add_u64 v[48:49], v[60:61], 0, s[2:3]
	v_cvt_pk_bf16_f32 v34, v28, v29
	v_cvt_pk_bf16_f32 v35, v30, v31
	global_store_dwordx4 v[60:61], v[64:67], off
	global_store_dwordx4 v[48:49], v[32:35], off offset:256
	v_cvt_pk_bf16_f32 v44, v56, v57
	v_cvt_pk_bf16_f32 v45, v58, v59
	v_lshl_add_u64 v[32:33], v[48:49], 0, s[2:3]
	v_cvt_pk_bf16_f32 v46, v52, v53
	v_cvt_pk_bf16_f32 v47, v54, v55
	v_cvt_pk_bf16_f32 v16, v16, v17
	v_cvt_pk_bf16_f32 v17, v18, v19
	v_cvt_pk_bf16_f32 v18, v12, v13
	v_cvt_pk_bf16_f32 v19, v14, v15
	global_store_dwordx4 v[48:49], v[44:47], off
	global_store_dwordx4 v[32:33], v[16:19], off offset:256
	v_cvt_pk_bf16_f32 v28, v40, v41
	v_cvt_pk_bf16_f32 v29, v42, v43
	v_lshl_add_u64 v[16:17], v[32:33], 0, s[2:3]
	v_cvt_pk_bf16_f32 v30, v36, v37
	v_cvt_pk_bf16_f32 v31, v38, v39
	v_cvt_pk_bf16_f32 v12, v24, v25
	v_cvt_pk_bf16_f32 v13, v26, v27
	v_cvt_pk_bf16_f32 v14, v20, v21
	v_cvt_pk_bf16_f32 v15, v22, v23
	v_cvt_pk_bf16_f32 v8, v8, v9
	v_cvt_pk_bf16_f32 v9, v10, v11
	v_cvt_pk_bf16_f32 v10, v4, v5
	v_cvt_pk_bf16_f32 v11, v6, v7
	s_and_b64 vcc, exec, s[6:7]
	s_mov_b64 s[2:3], s[14:15]
	s_mov_b64 s[16:17], s[12:13]
	s_mov_b64 s[8:9], s[10:11]
	s_mov_b32 s4, s56
	s_mov_b32 s5, s28
	global_store_dwordx4 v[32:33], v[28:31], off
	global_store_dwordx4 v[16:17], v[12:15], off
	global_store_dwordx4 v[16:17], v[8:11], off offset:256
	s_cbranch_vccz .LBB0_726
	s_waitcnt vmcnt(0)
	s_movk_i32 s66, 0x100
	v_cmp_gt_u32_e32 vcc, s66, v135
	s_and_saveexec_b64 s[0:1], vcc
	s_cbranch_execz .LBB0_733
	s_barrier
